# stick-breaking loop: logf tail as one f32 multiply (log2*ln2), dead code removed; on top of v21
# baseline (speedup 1.0000x reference)
; DI int crow(int i, int hi) { return (i & 3) + 8 * (i >> 2) + 4 * hi; }
; DI f32x16 mfma32(bf16x8 a, bf16x8 b, f32x16 c) { return __builtin_amdgcn_mfma_f32_32x32x16_bf16(a, b, c, 0, 0, 0); }
; DI void sb_unit(const bf16_t* QKV, bf16_t* ATT, LAS unsigned char* lds3, int b, int head, int qb, int wid, int lane) {
;     ...
;         f32x16 s;
; #pragma unroll
;         for (int i = 0; i < 16; ++i) s[i] = 0.f;
;         s = mfma32(kc0, qf[0], s); s = mfma32(kc1, qf[1], s); s = mfma32(kc2, qf[2], s); s = mfma32(kc3, qf[3], s);
;         const int qpos = q0 + r32;
;         float lk[16];
; #pragma unroll
;         for (int i = 0; i < 16; ++i) {
;             const float z = s[i] * 0.125f;
;             const bool past = (k0 + crow(i, hi)) < qpos;
;             const float sp = fmaxf(z, 0.f) + __logf(1.f + __expf(-fabsf(z)));
;             lk[i] = past ? -sp : 0.f;
;             s[i] = past ? z : -INFINITY;
;         }
.LBB0_312:
	v_mfma_f32_32x32x16_bf16 v[32:47], v[32:35], v[60:63], 0
	s_waitcnt lgkmcnt(0)
	v_mfma_f32_32x32x16_bf16 v[32:47], v[104:107], v[56:59], v[32:47]
	v_mfma_f32_32x32x16_bf16 v[32:47], v[100:103], v[52:55], v[32:47]
	v_add_u32_e32 v100, s20, v112
	v_add_u32_e32 v101, 32, v100
	v_add_u32_e32 v102, 33, v100
	v_or_b32_e32 v160, 17, v101
	v_or_b32_e32 v158, 24, v101
	v_or_b32_e32 v159, 16, v101
	v_cmp_lt_i32_e64 s[12:13], v158, v109
	v_mfma_f32_32x32x16_bf16 v[32:47], v[96:99], v[48:51], v[32:47]
	v_or_b32_e32 v161, 26, v101
	v_or_b32_e32 v162, 27, v101
	s_nop 9
	v_mul_f32_e32 v32, 0x3e000000, v32
	v_mul_f32_e32 v33, 0x3e000000, v33
	v_mul_f32_e64 v97, |v32|, s29
	v_mul_f32_e64 v98, |v33|, s29
	v_exp_f32_e32 v97, v97
	v_exp_f32_e32 v98, v98
	v_mul_f32_e32 v34, 0x3e000000, v34
	v_mul_f32_e64 v99, |v34|, s29
	v_add_f32_e32 v97, 1.0, v97
	v_add_f32_e32 v98, 1.0, v98
	v_cmp_gt_f32_e32 vcc, s30, v97
	v_cmp_gt_f32_e64 s[6:7], s30, v98
	v_exp_f32_e32 v99, v99
	v_cndmask_b32_e64 v104, 0, 32, vcc
	v_cndmask_b32_e64 v105, 0, 32, s[6:7]
	v_ldexp_f32 v97, v97, v104
	v_ldexp_f32 v98, v98, v105
	v_log_f32_e32 v97, v97
	v_log_f32_e32 v98, v98
	v_cndmask_b32_e32 v104, 0, v138, vcc
	v_add_f32_e32 v99, 1.0, v99
	v_cndmask_b32_e64 v105, 0, v138, s[6:7]
	v_mul_f32_e32 v97, 0x3f317217, v97
	v_cmp_gt_f32_e64 s[6:7], s30, v99
	v_max_f32_e32 v96, 0, v32
	v_mul_f32_e32 v98, 0x3f317217, v98
	v_cmp_lt_i32_e32 vcc, v101, v134
	v_sub_f32_e32 v97, v97, v104
	v_max_f32_e32 v103, 0, v33
	v_cndmask_b32_e32 v104, v139, v32, vcc
	v_cndmask_b32_e64 v32, 0, 32, s[6:7]
	v_ldexp_f32 v32, v99, v32
	v_log_f32_e32 v32, v32
	v_sub_f32_e32 v98, v98, v105
	v_add_f32_e32 v96, v96, v97
	v_add_f32_e32 v97, v103, v98
	v_cndmask_b32_e64 v103, 0, -v96, vcc
	v_cmp_lt_i32_e32 vcc, v102, v134
	v_mul_f32_e32 v35, 0x3e000000, v35
	v_max_f32_e32 v96, 0, v34
	v_cndmask_b32_e64 v102, 0, -v97, vcc
	v_cndmask_b32_e32 v105, v139, v33, vcc
	v_add_u32_e32 v33, 34, v100
	v_mul_f32_e32 v36, 0x3e000000, v36
	v_mul_f32_e32 v32, 0x3f317217, v32
	v_cndmask_b32_e64 v97, 0, v138, s[6:7]
	v_sub_f32_e32 v32, v32, v97
	v_mul_f32_e64 v97, |v35|, s29
	v_exp_f32_e32 v97, v97
	v_add_f32_e32 v32, v96, v32
	v_cmp_lt_i32_e32 vcc, v33, v134
	v_mul_f32_e32 v99, 0x3e000000, v40
	v_mul_f32_e32 v151, 0x3e000000, v42
	v_cndmask_b32_e64 v106, 0, -v32, vcc
	v_add_f32_e32 v32, 1.0, v97
	v_cmp_gt_f32_e64 s[6:7], s30, v32
	v_cndmask_b32_e32 v107, v139, v34, vcc
	v_max_f32_e32 v34, 0, v35
	v_cndmask_b32_e64 v33, 0, 32, s[6:7]
	v_ldexp_f32 v32, v32, v33
	v_log_f32_e32 v32, v32
	v_add_u32_e32 v33, 35, v100
	v_mul_f32_e32 v152, 0x3e000000, v43
	v_mul_f32_e32 v153, 0x3e000000, v44
	v_mul_f32_e32 v154, 0x3e000000, v45
	v_mul_f32_e32 v155, 0x3e000000, v46
	v_mul_f32_e32 v32, 0x3f317217, v32
	v_cndmask_b32_e64 v96, 0, v138, s[6:7]
	v_sub_f32_e32 v32, v32, v96
	v_mul_f32_e64 v96, |v36|, s29
	v_exp_f32_e32 v96, v96
	v_add_f32_e32 v32, v34, v32
	v_cmp_lt_i32_e32 vcc, v33, v134
	v_max_f32_e32 v34, 0, v36
	v_mul_f32_e64 v43, |v155|, s29
	v_cndmask_b32_e64 v141, 0, -v32, vcc
	v_add_f32_e32 v32, 1.0, v96
	v_cmp_gt_f32_e64 s[6:7], s30, v32
	v_cndmask_b32_e32 v142, v139, v35, vcc
	v_exp_f32_e32 v43, v43
	v_cndmask_b32_e64 v33, 0, 32, s[6:7]
	v_ldexp_f32 v32, v32, v33
	v_log_f32_e32 v32, v32
	v_add_u32_e32 v33, 40, v100
	v_mul_f32_e32 v47, 0x3e000000, v47
	v_mul_f32_e64 v46, |v47|, s29
	v_exp_f32_e32 v46, v46
	v_max_f32_e32 v40, 0, v151
	v_mul_f32_e32 v32, 0x3f317217, v32
	v_cndmask_b32_e64 v35, 0, v138, s[6:7]
	v_sub_f32_e32 v32, v32, v35
	v_mul_f32_e32 v35, 0x3e000000, v37
	v_mul_f32_e64 v37, |v35|, s29
	v_exp_f32_e32 v37, v37
	v_add_f32_e32 v32, v34, v32
	v_cmp_lt_i32_e32 vcc, v33, v134
	v_max_f32_e32 v34, 0, v35
	v_max_f32_e32 v96, 0, v152
	v_cndmask_b32_e64 v143, 0, -v32, vcc
	v_add_f32_e32 v32, 1.0, v37
	v_cmp_gt_f32_e64 s[6:7], s30, v32
	v_cndmask_b32_e32 v144, v139, v36, vcc
	v_max_f32_e32 v97, 0, v47
	v_cndmask_b32_e64 v33, 0, 32, s[6:7]
	v_ldexp_f32 v32, v32, v33
	v_log_f32_e32 v32, v32
	v_add_u32_e32 v33, 41, v100
	v_add_f32_e32 v98, v106, v141
	s_nop 1
	v_mul_f32_e32 v32, 0x3f317217, v32
	v_cndmask_b32_e64 v36, 0, v138, s[6:7]
	v_sub_f32_e32 v32, v32, v36
	v_mul_f32_e32 v36, 0x3e000000, v38
	v_mul_f32_e64 v37, |v36|, s29
	v_exp_f32_e32 v37, v37
	v_add_f32_e32 v32, v34, v32
	v_cmp_lt_i32_e32 vcc, v33, v134
	v_max_f32_e32 v34, 0, v36
	s_nop 0
	v_cndmask_b32_e64 v145, 0, -v32, vcc
	v_add_f32_e32 v32, 1.0, v37
	v_cmp_gt_f32_e64 s[6:7], s30, v32
	v_cndmask_b32_e32 v146, v139, v35, vcc
	s_nop 0
	v_cndmask_b32_e64 v33, 0, 32, s[6:7]
	v_ldexp_f32 v32, v32, v33
	v_log_f32_e32 v32, v32
	v_add_u32_e32 v33, 42, v100
	s_nop 1
	v_mul_f32_e32 v32, 0x3f317217, v32
	v_cndmask_b32_e64 v35, 0, v138, s[6:7]
	v_sub_f32_e32 v32, v32, v35
	v_mul_f32_e32 v35, 0x3e000000, v39
	v_mul_f32_e64 v37, |v35|, s29
	v_exp_f32_e32 v37, v37
	v_add_f32_e32 v32, v34, v32
	v_cmp_lt_i32_e32 vcc, v33, v134
	v_max_f32_e32 v34, 0, v35
	v_mul_f32_e64 v39, |v154|, s29
	v_cndmask_b32_e64 v147, 0, -v32, vcc
	v_add_f32_e32 v32, 1.0, v37
	v_cmp_gt_f32_e64 s[6:7], s30, v32
	v_cndmask_b32_e32 v148, v139, v36, vcc
	v_exp_f32_e32 v39, v39
	v_cndmask_b32_e64 v33, 0, 32, s[6:7]
	v_ldexp_f32 v32, v32, v33
	v_log_f32_e32 v32, v32
	v_cndmask_b32_e64 v37, 0, v138, s[6:7]
	v_add_u32_e32 v33, 43, v100
	v_cmp_lt_i32_e64 s[6:7], v33, v134
	v_mul_f32_e32 v100, 0x3e000000, v41
	v_cndmask_b32_e64 v150, v139, v35, s[6:7]
	v_mul_f32_e32 v32, 0x3f317217, v32
	v_mul_f32_e64 v36, |v99|, s29
	v_exp_f32_e32 v36, v36
	v_sub_f32_e32 v32, v32, v37
	v_add_f32_e32 v32, v34, v32
	v_mul_f32_e64 v35, |v100|, s29
	v_add_f32_e32 v34, 1.0, v36
	v_cmp_gt_f32_e32 vcc, s30, v34
	v_exp_f32_e32 v35, v35
; DI float xhalf(float v) { return __shfl_xor(v, 32); }
; DI int crow(int i, int hi) { return (i & 3) + 8 * (i >> 2) + 4 * hi; }
; DI void sb_unit(const bf16_t* QKV, bf16_t* ATT, LAS unsigned char* lds3, int b, int head, int qb, int wid, int lane) {
;     ...
;         for (int i = 0; i < 16; ++i) {
;             const float z = s[i] * 0.125f;
;             const bool past = (k0 + crow(i, hi)) < qpos;
;             const float sp = fmaxf(z, 0.f) + __logf(1.f + __expf(-fabsf(z)));
;             lk[i] = past ? -sp : 0.f;
;             s[i] = past ? z : -INFINITY;
;         }
;         float gs[4], go[4];
; #pragma unroll
;         for (int g = 0; g < 4; ++g) { gs[g] = (lk[4 * g] + lk[4 * g + 1]) + (lk[4 * g + 2] + lk[4 * g + 3]); go[g] = xhalf(gs[g]); }
	v_cndmask_b32_e64 v149, 0, -v32, s[6:7]
	v_cndmask_b32_e64 v36, 0, 32, vcc
	v_ldexp_f32 v34, v34, v36
	v_log_f32_e32 v34, v34
	v_mul_f32_e64 v37, |v151|, s29
	v_exp_f32_e32 v37, v37
	v_max_f32_e32 v32, 0, v99
	v_mul_f32_e32 v33, 0x3f317217, v34
	v_fma_f32 v33, v34, s31, -v33
	v_fmac_f32_e32 v33, 0x3377d1cf, v34
	v_fmac_f32_e32 v33, 0x3f317217, v34
	v_cmp_lt_f32_e64 s[6:7], |v34|, s33
	v_max_f32_e32 v36, 0, v100
	s_nop 0
	v_cndmask_b32_e64 v33, v34, v33, s[6:7]
	v_add_f32_e32 v34, 1.0, v35
	v_cmp_gt_f32_e64 s[6:7], s30, v34
	s_nop 1
	v_cndmask_b32_e64 v35, 0, 32, s[6:7]
	v_ldexp_f32 v34, v34, v35
	v_log_f32_e32 v35, v34
	v_cndmask_b32_e32 v34, 0, v138, vcc
	v_sub_f32_e32 v34, v33, v34
	s_nop 1
	v_mul_f32_e32 v33, 0x3f317217, v35
	v_add_f32_e32 v35, 1.0, v37
	v_cmp_gt_f32_e32 vcc, s30, v35
	s_nop 1
	v_cndmask_b32_e64 v37, 0, 32, vcc
	v_ldexp_f32 v35, v35, v37
	v_log_f32_e32 v35, v35
	v_cndmask_b32_e64 v37, 0, v138, s[6:7]
	v_sub_f32_e32 v38, v33, v37
	v_mul_f32_e64 v37, |v152|, s29
	v_mul_f32_e32 v33, 0x3f317217, v35
	v_exp_f32_e32 v37, v37
	v_fma_f32 v33, v35, s31, -v33
	v_fmac_f32_e32 v33, 0x3377d1cf, v35
	v_fmac_f32_e32 v33, 0x3f317217, v35
	v_cmp_lt_f32_e64 s[6:7], |v35|, s33
	s_nop 1
	v_cndmask_b32_e64 v33, v35, v33, s[6:7]
	v_add_f32_e32 v35, 1.0, v37
	v_cmp_gt_f32_e64 s[6:7], s30, v35
	s_nop 1
	v_cndmask_b32_e64 v37, 0, 32, s[6:7]
	v_ldexp_f32 v35, v35, v37
	v_log_f32_e32 v35, v35
	v_cndmask_b32_e32 v37, 0, v138, vcc
	v_sub_f32_e32 v42, v33, v37
	v_mul_f32_e64 v37, |v153|, s29
	v_exp_f32_e32 v37, v37
	s_nop 1
	v_mul_f32_e32 v33, 0x3f317217, v35
	v_add_f32_e32 v35, 1.0, v37
	v_cmp_gt_f32_e32 vcc, s30, v35
	s_nop 1
	v_cndmask_b32_e64 v37, 0, 32, vcc
	v_ldexp_f32 v35, v35, v37
	v_log_f32_e32 v35, v35
	v_cndmask_b32_e64 v37, 0, v138, s[6:7]
	v_sub_f32_e32 v44, v33, v37
	v_max_f32_e32 v33, 0, v153
	v_mul_f32_e32 v37, 0x3f317217, v35
	v_fma_f32 v37, v35, s31, -v37
	v_fmac_f32_e32 v37, 0x3377d1cf, v35
	v_fmac_f32_e32 v37, 0x3f317217, v35
	v_cmp_lt_f32_e64 s[6:7], |v35|, s33
	s_nop 1
	v_cndmask_b32_e64 v35, v35, v37, s[6:7]
	v_add_f32_e32 v37, 1.0, v39
	v_cmp_gt_f32_e64 s[6:7], s30, v37
	s_nop 1
	v_cndmask_b32_e64 v39, 0, 32, s[6:7]
	v_ldexp_f32 v37, v37, v39
	v_log_f32_e32 v39, v37
	v_cndmask_b32_e32 v37, 0, v138, vcc
	v_sub_f32_e32 v35, v35, v37
	v_max_f32_e32 v37, 0, v154
	v_pk_add_f32 v[32:33], v[32:33], v[34:35]
	s_nop 0
	v_mul_f32_e32 v39, 0x3f317217, v39
	v_add_f32_e32 v41, 1.0, v43
	v_cmp_gt_f32_e32 vcc, s30, v41
	s_nop 1
	v_cndmask_b32_e64 v43, 0, 32, vcc
	v_ldexp_f32 v41, v41, v43
	v_log_f32_e32 v43, v41
	v_cndmask_b32_e64 v41, 0, v138, s[6:7]
	v_sub_f32_e32 v39, v39, v41
	v_max_f32_e32 v41, 0, v155
	v_mul_f32_e32 v45, 0x3f317217, v43
	v_fma_f32 v45, v43, s31, -v45
	v_fmac_f32_e32 v45, 0x3377d1cf, v43
	v_fmac_f32_e32 v45, 0x3f317217, v43
	v_cmp_lt_f32_e64 s[6:7], |v43|, s33
	s_nop 1
	v_cndmask_b32_e64 v43, v43, v45, s[6:7]
	v_add_f32_e32 v45, 1.0, v46
	v_cmp_gt_f32_e64 s[6:7], s30, v45
	s_nop 1
	v_cndmask_b32_e64 v46, 0, 32, s[6:7]
	v_ldexp_f32 v45, v45, v46
	v_log_f32_e32 v45, v45
	v_cndmask_b32_e32 v46, 0, v138, vcc
	v_sub_f32_e32 v43, v43, v46
	v_pk_add_f32 v[34:35], v[40:41], v[42:43]
	v_cndmask_b32_e64 v42, v139, v153, s[12:13]
	s_nop 0
	v_mul_f32_e32 v45, 0x3f317217, v45
	v_cndmask_b32_e64 v46, 0, v138, s[6:7]
	v_cmp_lt_i32_e64 s[6:7], v160, v134
	v_cmp_lt_i32_e32 vcc, v159, v134
	v_sub_f32_e32 v45, v45, v46
	v_cndmask_b32_e64 v160, v139, v100, s[6:7]
	v_or_b32_e32 v100, 18, v101
	v_cmp_lt_i32_e64 s[8:9], v100, v134
	v_or_b32_e32 v100, 19, v101
	v_cndmask_b32_e32 v159, v139, v99, vcc
	v_or_b32_e32 v99, 25, v101
	v_cmp_lt_i32_e64 s[10:11], v100, v134
	v_cndmask_b32_e64 v101, 0, -v33, s[12:13]
	v_cndmask_b32_e64 v100, 0, -v32, vcc
	v_pk_add_f32 v[32:33], v[36:37], v[38:39]
	v_cndmask_b32_e64 v151, v139, v151, s[8:9]
	v_cmp_lt_i32_e32 vcc, v99, v109
	v_cndmask_b32_e64 v32, 0, -v32, s[6:7]
	v_cmp_lt_i32_e64 s[6:7], v161, v109
	v_cndmask_b32_e64 v34, 0, -v34, s[8:9]
	v_pk_add_f32 v[36:37], v[96:97], v[44:45]
	v_cmp_lt_i32_e64 s[8:9], v162, v109
	v_cndmask_b32_e64 v33, 0, -v33, vcc
	v_cndmask_b32_e64 v35, 0, -v35, s[6:7]
	v_cndmask_b32_e64 v37, 0, -v37, s[8:9]
	v_cndmask_b32_e64 v36, 0, -v36, s[10:11]
	v_pk_add_f32 v[38:39], v[100:101], v[32:33]
	v_pk_add_f32 v[40:41], v[34:35], v[36:37]
	v_add_f32_e32 v46, v103, v102
	v_pk_add_f32 v[38:39], v[38:39], v[40:41]
	v_add_f32_e32 v156, v46, v98
	v_add_f32_e32 v46, v143, v145
	v_add_f32_e32 v98, v147, v149
	ds_bpermute_b32 v40, v140, v38
	ds_bpermute_b32 v41, v140, v39
	v_add_f32_e32 v46, v46, v98
	ds_bpermute_b32 v98, v140, v46
	ds_bpermute_b32 v157, v140, v156
	v_cndmask_b32_e64 v45, v139, v47, s[8:9]
	s_waitcnt lgkmcnt(2)
; DI float xhalf(float v) { return __shfl_xor(v, 32); }
; DI f32x16 mfma32(bf16x8 a, bf16x8 b, f32x16 c) { return __builtin_amdgcn_mfma_f32_32x32x16_bf16(a, b, c, 0, 0, 0); }
; DI bf16x8 vfrag(LAS unsigned char* p) { const s16x4 lo = tr_read(p), hi = tr_read(p + 512); return __builtin_shufflevector(lo, hi, 0, 1, 2, 3, 4, 5, 6, 7); }
; DI void sb_unit(const bf16_t* QKV, bf16_t* ATT, LAS unsigned char* lds3, int b, int head, int qb, int wid, int lane) {
;     ...
;         float gs[4], go[4];
; #pragma unroll
;         for (int g = 0; g < 4; ++g) { gs[g] = (lk[4 * g] + lk[4 * g + 1]) + (lk[4 * g + 2] + lk[4 * g + 3]); go[g] = xhalf(gs[g]); }
;         const float ps0 = gs[0] + go[0], ps1 = gs[1] + go[1], ps2 = gs[2] + go[2], ps3 = gs[3] + go[3];
;         float ap[4]; ap[3] = 0.f; ap[2] = ps3; ap[1] = ps3 + ps2; ap[0] = ps3 + ps2 + ps1;
; #pragma unroll
;         for (int g = 0; g < 4; ++g) {
;             const float aft = carry + ap[g] + (hi == 0 ? go[g] : 0.f);
;             const float w3 = aft, w2 = aft + lk[4 * g + 3], w1 = w2 + lk[4 * g + 2], w0 = w1 + lk[4 * g + 1];
;             s[4 * g + 3] = __expf(s[4 * g + 3] + lk[4 * g + 3] + w3);
;             s[4 * g + 2] = __expf(s[4 * g + 2] + lk[4 * g + 2] + w2);
;             s[4 * g + 1] = __expf(s[4 * g + 1] + lk[4 * g + 1] + w1);
;             s[4 * g + 0] = __expf(s[4 * g + 0] + lk[4 * g + 0] + w0);
;         }
;         carry += (ps0 + ps1) + (ps2 + ps3);
;         const bf16x8 p0 = packP<0>(s), p1 = packP<1>(s);
;         asm volatile("s_waitcnt lgkmcnt(0)" ::: "memory");
; #pragma unroll
;         for (int dt = 0; dt < 2; ++dt) {
;             const bf16x8 v0 = vfrag(vrd + dt * 2048), v1 = vfrag(vrd + dt * 2048 + 1024);
;             o[dt] = mfma32(v0, p0, o[dt]); o[dt] = mfma32(v1, p1, o[dt]);
;         }
;         asm volatile("s_waitcnt lgkmcnt(0)" ::: "memory");
;         if (__all(carry < -104.f)) break;
	v_pk_add_f32 v[38:39], v[38:39], v[40:41]
	v_cndmask_b32_e64 v40, 0, v40, s[4:5]
	v_mov_b32_e32 v47, v38
	v_mov_b32_e32 v99, v39
	s_waitcnt lgkmcnt(1)
	v_pk_add_f32 v[96:97], v[46:47], v[98:99]
	s_waitcnt lgkmcnt(0)
	v_cndmask_b32_e64 v46, 0, v157, s[4:5]
	v_add_f32_e32 v38, v96, v97
	v_add_f32_e32 v38, v127, v38
	v_add_f32_e32 v38, v46, v38
	v_add_f32_e32 v46, v141, v38
	v_add_f32_e32 v47, v106, v46
	v_add_f32_e32 v99, v102, v47
	v_add_f32_e32 v102, v105, v102
	v_add_f32_e32 v47, v102, v47
	v_add_f32_e32 v102, v104, v103
	v_add_f32_e32 v99, v102, v99
	v_add_f32_e32 v102, v127, v97
	v_cndmask_b32_e64 v98, 0, v98, s[4:5]
	v_add_f32_e32 v98, v98, v102
	v_add_f32_e32 v105, v150, v149
	v_add_f32_e32 v102, v149, v98
	v_add_f32_e32 v98, v105, v98
	v_add_f32_e32 v105, v148, v147
	v_add_f32_e32 v39, v127, v39
	v_add_f32_e32 v103, v147, v102
	v_add_f32_e32 v102, v105, v102
	v_add_f32_e32 v105, v146, v145
	v_add_f32_e32 v39, v40, v39
	v_add_f32_e32 v104, v145, v103
	v_add_f32_e32 v103, v105, v103
	v_add_f32_e32 v105, v144, v143
	v_add_f32_e32 v40, v36, v39
	v_add_f32_e32 v106, v107, v106
	v_add_f32_e32 v104, v105, v104
	v_add_f32_e32 v105, v34, v40
	v_add_f32_e32 v46, v106, v46
	v_add_f32_e32 v106, v32, v105
	v_add_f32_e32 v32, v160, v32
	v_add_f32_e32 v32, v32, v105
	v_mul_f32_e32 v32, 0x3fb8aa3b, v32
	v_add_f32_e32 v34, v151, v34
	v_exp_f32_e32 v105, v32
	v_add_f32_e32 v32, v159, v100
	v_add_f32_e32 v34, v34, v40
	v_add_f32_e32 v32, v32, v106
	v_add_f32_e32 v141, v142, v141
	v_mul_f32_e32 v34, 0x3fb8aa3b, v34
	v_mul_f32_e32 v32, 0x3fb8aa3b, v32
	v_add_f32_e32 v38, v141, v38
	v_exp_f32_e32 v141, v34
	v_exp_f32_e32 v100, v32
	v_add_f32_e32 v32, 0, v127
	v_cndmask_b32_e64 v34, 0, v41, s[4:5]
	v_add_f32_e32 v32, v32, v34
	v_add_f32_e32 v34, v32, v37
	v_add_f32_e32 v37, v45, v37
	v_cndmask_b32_e64 v152, v139, v152, s[10:11]
	v_add_f32_e32 v32, v32, v37
	v_cndmask_b32_e64 v44, v139, v155, s[6:7]
	v_add_f32_e32 v36, v152, v36
	v_mul_f32_e32 v32, 0x3fb8aa3b, v32
	v_add_f32_e32 v36, v36, v39
	v_exp_f32_e32 v45, v32
	v_add_f32_e32 v32, v44, v35
	v_cndmask_b32_e32 v43, v139, v154, vcc
	v_mul_f32_e32 v36, 0x3fb8aa3b, v36
	v_add_f32_e32 v32, v34, v32
	v_exp_f32_e32 v107, v36
	v_add_f32_e32 v36, v35, v34
	v_mul_f32_e32 v44, 0x3fb8aa3b, v32
	v_add_f32_e32 v32, v43, v33
	v_add_f32_e32 v32, v32, v36
	v_mul_f32_e32 v38, 0x3fb8aa3b, v38
	v_mul_f32_e32 v46, 0x3fb8aa3b, v46
	v_mul_f32_e32 v47, 0x3fb8aa3b, v47
	v_mul_f32_e32 v99, 0x3fb8aa3b, v99
	v_mul_f32_e32 v98, 0x3fb8aa3b, v98
	v_mul_f32_e32 v102, 0x3fb8aa3b, v102
	v_mul_f32_e32 v103, 0x3fb8aa3b, v103
	v_mul_f32_e32 v104, 0x3fb8aa3b, v104
	v_mul_f32_e32 v32, 0x3fb8aa3b, v32
	v_exp_f32_e32 v38, v38
	v_exp_f32_e32 v46, v46
	v_exp_f32_e32 v47, v47
	v_exp_f32_e32 v99, v99
	v_exp_f32_e32 v98, v98
	v_exp_f32_e32 v102, v102
	v_exp_f32_e32 v103, v103
	v_exp_f32_e32 v104, v104
	v_add_f32_e32 v39, v33, v36
	v_exp_f32_e32 v106, v32
	ds_read_b64_tr_b16 v[32:33], v115
	ds_read_b64_tr_b16 v[34:35], v115 offset:512
	v_add_f32_e32 v36, v42, v101
	v_add_f32_e32 v101, v36, v39
	v_cvt_pk_bf16_f32 v36, v99, v47
	v_cvt_pk_bf16_f32 v37, v46, v38
	v_cvt_pk_bf16_f32 v38, v104, v103
	v_cvt_pk_bf16_f32 v39, v102, v98
	ds_read_b64_tr_b16 v[40:41], v115 offset:1024
	ds_read_b64_tr_b16 v[42:43], v115 offset:1536
	s_waitcnt lgkmcnt(2)
	v_mfma_f32_32x32x16_bf16 v[16:31], v[32:35], v[36:39], v[16:31]
	v_mul_f32_e32 v32, 0x3fb8aa3b, v101
	v_exp_f32_e32 v34, v32
	v_exp_f32_e32 v35, v44
	v_cvt_pk_bf16_f32 v32, v100, v105
	v_cvt_pk_bf16_f32 v33, v141, v107
	v_cvt_pk_bf16_f32 v34, v34, v106
	v_cvt_pk_bf16_f32 v35, v35, v45
	s_mov_b64 s[6:7], -1
	s_mov_b64 s[8:9], -1
	s_waitcnt lgkmcnt(0)
	v_mfma_f32_32x32x16_bf16 v[16:31], v[40:43], v[32:35], v[16:31]
	ds_read_b64_tr_b16 v[40:41], v115 offset:2048
	ds_read_b64_tr_b16 v[42:43], v115 offset:2560
	ds_read_b64_tr_b16 v[44:45], v115 offset:3072
	ds_read_b64_tr_b16 v[46:47], v115 offset:3584
	s_waitcnt lgkmcnt(0)
	s_waitcnt lgkmcnt(2)
	v_mfma_f32_32x32x16_bf16 v[0:15], v[40:43], v[36:39], v[0:15]
	v_add_f32_e32 v36, v156, v157
	v_add_f32_e32 v36, v36, v96
	v_add_f32_e32 v36, v36, v97
	v_add_f32_e32 v127, v127, v36
	v_cmp_gt_f32_e32 vcc, s34, v127
	s_cmp_lg_u64 vcc, exec
	s_waitcnt lgkmcnt(0)
	v_mfma_f32_32x32x16_bf16 v[0:15], v[44:47], v[32:35], v[0:15]
	s_cbranch_scc0 .LBB0_314
	s_sub_i32 s20, s20, 32
	s_cmpk_eq_i32 s20, 0xffc0
	s_mov_b64 s[6:7], 0
	s_cselect_b64 s[8:9], -1, 0
